# selected-block stream staged HBM->LDS directly (global_load_lds_dwordx4 one stage ahead, row permutation + XOR swizzle moved to per-lane source offsets) instead of registers + ds_write_b128; on top of
# speedup vs baseline: 1.0187x; 1.0129x over previous
; #define LAS __attribute__((address_space(3)))
; __device__ __forceinline__ int launder_v(int x) { asm volatile("" : "+v"(x)); return x; }
; __device__ __forceinline__ int launder_s(int x) { x = __builtin_amdgcn_readfirstlane(x); asm volatile("" : "+s"(x)); return x; }
; template <int STG, class F>
; __device__ __forceinline__ void stream_tiles(Ctx& C, const TileSrc& src, int tile0, int ntiles, LAS unsigned char* bufs, F&& compute) {
;     if (ntiles <= 0) return;
;     const int nst = (ntiles + STG - 1) / STG, tlast = tile0 + ntiles - 1;
;     v4u rk[STG], rv[STG];
;     { const int tidl = launder_v(C.tid);
; #pragma unroll
;       for (int h = 0; h < STG; ++h) { const int t = tile0 + h; tile_fetch(src, 64 * (t < tlast ? t : tlast), tidl, rk[h], rv[h]); }
; #pragma unroll
;       for (int h = 0; h < STG; ++h) tile_store(bufs + h * 16384, tidl, rk[h], rv[h]); }
;     __syncthreads();
; __device__ __forceinline__ void nsa_block_task(Ctx& C, int task, bf16* ONSA_OUT) {
;     ...
;         for (int c = 0; c < 4; ++c) STASH[(cg * 4 + c) * 64 + lane] = oc[cg][c];
;     __syncthreads();
;     {
;         AttnAcc a[2]; attn_init(a[0]); attn_init(a[1]);
;         const int kvs = launder_s(kvh);
;         const TileSrc src{WSP(bf16, WS_KS) + (size_t)kvs * RP * 64, WSP(bf16, WS_VST) + (size_t)kvs * 64 * RP, RP};
;         int cw = -1; unsigned aw0 = 0u, aw1 = 0u;
;         stream_tiles<4>(C, src, 0, qb, bufs, [&](const LAS unsigned char* buf, int j) {
.LBB0_1206:
	s_or_b64 exec, exec, s[16:17]
	v_pk_mul_f32 v[32:33], v[186:187], v[32:33] op_sel_hi:[0,1]
	v_pk_mul_f32 v[34:35], v[186:187], v[34:35] op_sel_hi:[0,1]
	s_mov_b32 s3, s97
	v_pk_mul_f32 v[48:49], v[186:187], v[48:49] op_sel_hi:[0,1]
	v_pk_mul_f32 v[50:51], v[186:187], v[50:51] op_sel_hi:[0,1]
	v_pk_mul_f32 v[44:45], v[186:187], v[44:45] op_sel_hi:[0,1]
	v_pk_mul_f32 v[46:47], v[186:187], v[46:47] op_sel_hi:[0,1]
	v_pk_mul_f32 v[36:37], v[182:183], v[36:37] op_sel_hi:[0,1]
	v_pk_mul_f32 v[38:39], v[182:183], v[38:39] op_sel_hi:[0,1]
	v_pk_mul_f32 v[40:41], v[182:183], v[40:41] op_sel_hi:[0,1]
	v_pk_mul_f32 v[42:43], v[182:183], v[42:43] op_sel_hi:[0,1]
	v_pk_mul_f32 v[28:29], v[186:187], v[28:29] op_sel_hi:[0,1]
	v_pk_mul_f32 v[30:31], v[186:187], v[30:31] op_sel_hi:[0,1]
	v_pk_mul_f32 v[20:21], v[182:183], v[20:21] op_sel_hi:[0,1]
	v_pk_mul_f32 v[22:23], v[182:183], v[22:23] op_sel_hi:[0,1]
	v_pk_mul_f32 v[24:25], v[182:183], v[24:25] op_sel_hi:[0,1]
	v_pk_mul_f32 v[26:27], v[182:183], v[26:27] op_sel_hi:[0,1]
	s_waitcnt lgkmcnt(0)
	global_store_dwordx4 v[200:201], v[32:35], off
	global_store_dwordx4 v[200:201], v[48:51], off offset:1024
	global_store_dwordx4 v[200:201], v[28:31], off offset:2048
	global_store_dwordx4 v[200:201], v[44:47], off offset:3072
	global_store_dwordx4 v[202:203], v[20:23], off
	global_store_dwordx4 v[202:203], v[36:39], off offset:1024
	global_store_dwordx4 v[202:203], v[24:27], off offset:2048
	global_store_dwordx4 v[202:203], v[40:43], off offset:3072
	s_waitcnt lgkmcnt(0)
	s_barrier
	s_mul_hi_i32 s17, s3, 0x208000
	s_mul_i32 s3, s3, 0x208000
	s_add_u32 s18, s79, s3
	s_addc_u32 s19, s80, s17
	s_add_u32 s16, s81, s3
	s_addc_u32 s17, s82, s17
	s_cmp_eq_u32 s94, 0
	s_mov_b32 s26, 0
	s_cbranch_scc1 .LBB0_1229
	v_mov_b32_e32 v36, v189
	s_add_i32 s3, s94, 3
	v_ashrrev_i32_e32 v20, 3, v36
	v_lshlrev_b32_e32 v28, 4, v36
	v_and_b32_e32 v0, 0x70, v28
	v_ashrrev_i32_e32 v21, 31, v20
	v_mov_b64_e32 v[22:23], s[16:17]
	v_lshl_add_u64 v[2:3], s[18:19], 0, v[0:1]
	v_mad_i64_i32 v[22:23], s[20:21], v20, s92, v[22:23]
	v_lshlrev_b64 v[24:25], 7, v[20:21]
	s_cmp_eq_u32 s0, 0
	v_lshl_add_u64 v[24:25], v[2:3], 0, v[24:25]
	s_cselect_b32 s20, 0, 64
	v_lshl_add_u64 v[22:23], v[22:23], 0, v[0:1]
	v_add_u32_e32 v24, s20, v20
	v_ashrrev_i32_e32 v25, 31, v24
	v_lshlrev_b64 v[24:25], 7, v[24:25]
	v_lshl_add_u64 v[24:25], v[2:3], 0, v[24:25]
	s_lshl_b32 s50, s20, 1
	s_min_u32 s20, s0, 2
	v_lshl_add_u64 v[26:27], v[22:23], 0, s[50:51]
	v_lshl_add_u32 v24, s20, 6, v20
	v_ashrrev_i32_e32 v25, 31, v24
	v_lshlrev_b64 v[24:25], 7, v[24:25]
	v_lshl_add_u64 v[24:25], v[2:3], 0, v[24:25]
	s_lshl_b32 s50, s20, 7
	s_min_u32 s20, s0, 3
	v_lshl_add_u64 v[26:27], v[22:23], 0, s[50:51]
	v_lshl_add_u32 v24, s20, 6, v20
	v_ashrrev_i32_e32 v25, 31, v24
	v_lshlrev_b64 v[24:25], 7, v[24:25]
	v_lshl_add_u64 v[2:3], v[2:3], 0, v[24:25]
	s_lshl_b32 s50, s20, 7
	v_lshl_add_u64 v[22:23], v[22:23], 0, s[50:51]
	v_lshrrev_b32_e32 v233, 3, v189
	v_and_b32_e32 v254, 7, v189
	v_bfe_u32 v174, v233, 1, 3
	v_xor_b32_e32 v254, v254, v174
	v_lshlrev_b32_e32 v254, 4, v254
	v_mul_lo_u32 v198, v233, s92
	v_add_u32_e32 v198, v198, v254
	v_and_b32_e32 v174, 32, v233
	v_bfe_u32 v175, v233, 2, 2
	v_lshl_or_b32 v174, v175, 3, v174
	v_bfe_u32 v175, v233, 4, 1
	v_lshl_or_b32 v174, v175, 2, v174
	v_and_or_b32 v174, v233, 3, v174
	v_lshl_add_u32 v185, v174, 7, v254
	v_readfirstlane_b32 s44, v189
	s_lshl_b32 s44, s44, 4
	s_mov_b32 s28, 0
	s_mov_b32 s3, 0
	s_add_i32 s45, s3, s44
	s_min_i32 s24, s28, s0
	s_add_i32 m0, s45, 0x0
	s_lshl_b32 s98, s24, 13
	s_add_u32 s98, s18, s98
	s_addc_u32 s99, s19, 0
	global_load_lds_dwordx4 v185, s[98:99]
	s_add_i32 m0, s45, 0x2000
	s_lshl_b32 s100, s24, 7
	s_add_u32 s100, s16, s100
	s_addc_u32 s101, s17, 0
	global_load_lds_dwordx4 v198, s[100:101]
	s_add_i32 s24, s28, 1
	s_min_i32 s24, s24, s0
	s_add_i32 m0, s45, 0x4000
	s_lshl_b32 s98, s24, 13
	s_add_u32 s98, s18, s98
	s_addc_u32 s99, s19, 0
	global_load_lds_dwordx4 v185, s[98:99]
	s_add_i32 m0, s45, 0x6000
	s_lshl_b32 s100, s24, 7
	s_add_u32 s100, s16, s100
	s_addc_u32 s101, s17, 0
	global_load_lds_dwordx4 v198, s[100:101]
	s_add_i32 s24, s28, 2
	s_min_i32 s24, s24, s0
	s_add_i32 m0, s45, 0x8000
	s_lshl_b32 s98, s24, 13
	s_add_u32 s98, s18, s98
	s_addc_u32 s99, s19, 0
	global_load_lds_dwordx4 v185, s[98:99]
	s_add_i32 m0, s45, 0xa000
	s_lshl_b32 s100, s24, 7
	s_add_u32 s100, s16, s100
	s_addc_u32 s101, s17, 0
	global_load_lds_dwordx4 v198, s[100:101]
	s_add_i32 s24, s28, 3
	s_min_i32 s24, s24, s0
	s_add_i32 m0, s45, 0xc000
	s_lshl_b32 s98, s24, 13
	s_add_u32 s98, s18, s98
	s_addc_u32 s99, s19, 0
	global_load_lds_dwordx4 v185, s[98:99]
	s_add_i32 m0, s45, 0xe000
	s_lshl_b32 s100, s24, 7
	s_add_u32 s100, s16, s100
	s_addc_u32 s101, s17, 0
	global_load_lds_dwordx4 v198, s[100:101]
	s_add_i32 s3, s94, 3
	v_lshlrev_b32_e32 v0, 2, v20
	v_lshrrev_b32_e32 v21, 1, v20
	v_mov_b32_e32 v2, v1
	v_mov_b32_e32 v3, v1
	v_and_b32_e32 v22, 35, v20
	v_lshlrev_b32_e32 v20, 7, v20
	v_bitop3_b32 v23, v28, s91, v36 bitop3:0x48
	v_and_b32_e32 v24, 16, v0
	v_and_b32_e32 v21, 12, v21
	v_add3_u32 v37, 0, v20, v23
	v_mov_b32_e32 v0, v1
	v_or3_b32 v38, v24, v22, v21
	v_mov_b64_e32 v[22:23], v[2:3]
	v_mov_b64_e32 v[26:27], v[2:3]
	v_mov_b64_e32 v[30:31], v[2:3]
	v_mov_b64_e32 v[34:35], v[2:3]
	v_mov_b64_e32 v[42:43], v[2:3]
	v_mov_b64_e32 v[46:47], v[2:3]
	v_mov_b64_e32 v[50:51], v[2:3]
	v_mov_b64_e32 v[54:55], v[2:3]
	v_mov_b64_e32 v[20:21], v[0:1]
	v_mov_b64_e32 v[24:25], v[0:1]
	v_mov_b64_e32 v[28:29], v[0:1]
	v_mov_b64_e32 v[32:33], v[0:1]
	v_mov_b64_e32 v[40:41], v[0:1]
	v_mov_b64_e32 v[44:45], v[0:1]
	v_mov_b64_e32 v[48:49], v[0:1]
	v_mov_b64_e32 v[52:53], v[0:1]
	v_lshrrev_b32_e32 v2, 1, v38
	v_xor_b32_e32 v2, v2, v36
	v_lshlrev_b32_e32 v2, 4, v2
	v_lshlrev_b32_e32 v0, 7, v38
	v_and_b32_e32 v2, 0x70, v2
	s_mov_b32 s27, 0
	v_mov_b32_e32 v169, 0xc4800000
	v_mov_b32_e32 v168, 0
	s_mov_b32 s22, -1
	s_mov_b32 s28, 0
	s_mov_b32 s31, 0
	s_mov_b32 s30, 0
	s_lshr_b32 s29, s3, 2
	v_add3_u32 v0, 0, v0, v2
	v_mov_b32_e32 v36, 0
	v_mov_b32_e32 v170, 0xc4800000
	s_mov_b32 s23, 0
	v_ashrrev_i32_e32 v226, 4, v190
	v_lshrrev_b32_e32 v225, 1, v190
	v_bitop3_b32 v233, v225, v226, 7 bitop3:0x6c
	v_lshlrev_b32_e32 v254, 7, v190
	v_add_u32_e32 v226, 4, v226
	v_lshlrev_b32_e32 v233, 4, v233
	v_and_b32_e32 v254, 0x780, v254
	v_bitop3_b32 v226, v226, v225, 7 bitop3:0x78
	v_lshlrev_b32_e32 v226, 4, v226
	v_add_u32_e32 v225, v254, v233
	v_add_u32_e32 v226, v254, v226
	s_waitcnt vmcnt(0) lgkmcnt(0)
	s_waitcnt lgkmcnt(0)
	s_barrier
; #define LAS __attribute__((address_space(3)))
; __device__ __forceinline__ int launder_v(int x) { asm volatile("" : "+v"(x)); return x; }
; template <int STG, class F>
; __device__ __forceinline__ void stream_tiles(Ctx& C, const TileSrc& src, int tile0, int ntiles, LAS unsigned char* bufs, F&& compute) {
;     ...
;     for (int st = 0; st < nst; ++st) {
;         const int tidl = launder_v(C.tid);
;         const bool more = st + 1 < nst;
;         if (more) {
; #pragma unroll
;             for (int h = 0; h < STG; ++h) { const int t = tile0 + STG * (st + 1) + h; tile_fetch(src, 64 * (t < tlast ? t : tlast), tidl, rk[h], rv[h]); } }
;         LAS unsigned char* cur = bufs + (st & 1) * (STG * 16384);
.LBB0_1208:
	s_add_i32 s34, s23, 1
	v_mov_b32_e32 v37, v189
	s_cmp_lt_u32 s34, s29
	s_cselect_b64 s[20:21], -1, 0
	v_ashrrev_i32_e32 v38, 3, v37
	v_lshlrev_b32_e32 v39, 4, v37
	s_cmp_ge_u32 s34, s29
	s_cbranch_scc1 .LBB0_1210
	s_lshl_b32 s3, s34, 2
	s_lshl_b32 s25, s34, 16
	s_and_b32 s25, s25, 0x10000
	s_add_i32 s45, s25, s44
	s_min_i32 s24, s3, s0
	s_add_i32 m0, s45, 0x0
	s_lshl_b32 s98, s24, 13
	s_add_u32 s98, s18, s98
	s_addc_u32 s99, s19, 0
	global_load_lds_dwordx4 v185, s[98:99]
	s_add_i32 m0, s45, 0x2000
	s_lshl_b32 s100, s24, 7
	s_add_u32 s100, s16, s100
	s_addc_u32 s101, s17, 0
	global_load_lds_dwordx4 v198, s[100:101]
	s_add_i32 s24, s3, 1
	s_min_i32 s24, s24, s0
	s_add_i32 m0, s45, 0x4000
	s_lshl_b32 s98, s24, 13
	s_add_u32 s98, s18, s98
	s_addc_u32 s99, s19, 0
	global_load_lds_dwordx4 v185, s[98:99]
	s_add_i32 m0, s45, 0x6000
	s_lshl_b32 s100, s24, 7
	s_add_u32 s100, s16, s100
	s_addc_u32 s101, s17, 0
	global_load_lds_dwordx4 v198, s[100:101]
	s_add_i32 s24, s3, 2
	s_min_i32 s24, s24, s0
	s_add_i32 m0, s45, 0x8000
	s_lshl_b32 s98, s24, 13
	s_add_u32 s98, s18, s98
	s_addc_u32 s99, s19, 0
	global_load_lds_dwordx4 v185, s[98:99]
	s_add_i32 m0, s45, 0xa000
	s_lshl_b32 s100, s24, 7
	s_add_u32 s100, s16, s100
	s_addc_u32 s101, s17, 0
	global_load_lds_dwordx4 v198, s[100:101]
	s_add_i32 s24, s3, 3
	s_min_i32 s24, s24, s0
	s_add_i32 m0, s45, 0xc000
	s_lshl_b32 s98, s24, 13
	s_add_u32 s98, s18, s98
	s_addc_u32 s99, s19, 0
	global_load_lds_dwordx4 v185, s[98:99]
	s_add_i32 m0, s45, 0xe000
	s_lshl_b32 s100, s24, 7
	s_add_u32 s100, s16, s100
	s_addc_u32 s101, s17, 0
	global_load_lds_dwordx4 v198, s[100:101]

; template <int STG, class F>
; __device__ __forceinline__ void stream_tiles(Ctx& C, const TileSrc& src, int tile0, int ntiles, LAS unsigned char* bufs, F&& compute) {
;     ...
;         if (more) {
; #pragma unroll
;             for (int h = 0; h < STG; ++h) tile_store(bufs + ((st + 1) & 1) * (STG * 16384) + h * 16384, tidl, rk[h], rv[h]); }
;         __syncthreads();
.LBB0_1225:
	s_andn2_b64 vcc, exec, s[20:21]
	s_cbranch_vccnz .LBB0_1227
	s_waitcnt vmcnt(0)
